# nt policy also on the w_in / mlp_in epilogue result stores (PB, VT, H streams)
# baseline (speedup 1.0000x reference)
; __device__ __forceinline__ unsigned cvt_pk_bf16(float lo, float hi) { const f32x2 v = (f32x2){lo, hi}; return __builtin_bit_cast(unsigned, __builtin_convertvector(v, bf16v2)); }
;     __device__ __forceinline__ void operator()(f32x4 (&acc)[2][2][4][2], const Unit& u, int wr, int wc, int fr, int fq, LAS unsigned char* xl, int wid, int lane) const {
;     ...
; #pragma unroll
;         for (int ai = 0; ai < 2; ++ai)
; #pragma unroll
;             for (int m = 0; m < 4; ++m) { bf16_t* rowp = base + (size_t)(row0 + ai * HALF + m * 16) * ldc + col0;
; #pragma unroll
;                 for (int bj = 0; bj < 2; ++bj) { f32x4 v0 = acc[ai][bj][m][0], v1 = acc[ai][bj][m][1];
;                     if (MODE == 2) {
; #pragma unroll
;                         for (int e = 0; e < 4; ++e) { const float a = fmaxf(v0[e], 0.f), b = fmaxf(v1[e], 0.f); v0[e] = a * a; v1[e] = b * b; } }
;                     u32x4 w; w.x = cvt_pk_bf16(v0[0], v0[1]); w.y = cvt_pk_bf16(v0[2], v0[3]); w.z = cvt_pk_bf16(v1[0], v1[1]); w.w = cvt_pk_bf16(v1[2], v1[3]);
;                     *(u32x4*)(rowp + bj * HALF) = w; } }
.LBB0_186:
	v_max_f32_e32 v120, 0, v120
	v_max_f32_e32 v121, 0, v121
	v_pk_mul_f32 v[148:149], v[120:121], v[120:121]
	v_lshl_add_u32 v144, s20, 8, v140
	v_lshl_or_b32 v138, s69, 8, v142
	v_max_f32_e32 v122, 0, v122
	v_ashrrev_i32_e32 v139, 31, v138
	v_ashrrev_i32_e32 v145, 31, v144
	v_max_f32_e32 v124, 0, v124
	v_max_f32_e32 v125, 0, v125
	v_max_f32_e32 v120, 0, v126
	v_max_f32_e32 v121, 0, v127
	v_max_f32_e32 v123, 0, v123
	v_lshl_add_u64 v[146:147], v[138:139], 1, s[8:9]
	v_lshlrev_b64 v[138:139], 13, v[144:145]
	v_pk_mul_f32 v[124:125], v[124:125], v[124:125]
	v_pk_mul_f32 v[126:127], v[120:121], v[120:121]
	v_pk_mul_f32 v[150:151], v[122:123], v[122:123]
	v_lshl_add_u64 v[138:139], v[146:147], 0, v[138:139]
	v_cvt_pk_bf16_f32 v120, v124, v125
	v_cvt_pk_bf16_f32 v121, v126, v127
	v_cvt_pk_bf16_f32 v122, v148, v149
	v_cvt_pk_bf16_f32 v123, v150, v151
	v_max_f32_e32 v112, 0, v112
	v_max_f32_e32 v113, 0, v113
	global_store_dwordx4 v[138:139], v[120:123], off nt
	s_nop 1
	v_pk_mul_f32 v[120:121], v[112:113], v[112:113]
	v_max_f32_e32 v114, 0, v114
	v_max_f32_e32 v116, 0, v116
	v_max_f32_e32 v117, 0, v117
	v_max_f32_e32 v112, 0, v118
	v_max_f32_e32 v113, 0, v119
	v_max_f32_e32 v115, 0, v115
	v_pk_mul_f32 v[116:117], v[116:117], v[116:117]
	v_pk_mul_f32 v[118:119], v[112:113], v[112:113]
	v_pk_mul_f32 v[122:123], v[114:115], v[114:115]
	v_cvt_pk_bf16_f32 v112, v116, v117
	v_cvt_pk_bf16_f32 v113, v118, v119
	v_cvt_pk_bf16_f32 v114, v120, v121
	v_cvt_pk_bf16_f32 v115, v122, v123
	v_max_f32_e32 v104, 0, v104
	v_max_f32_e32 v105, 0, v105
	global_store_dwordx4 v[138:139], v[112:115], off offset:256 nt
	s_nop 1
	v_pk_mul_f32 v[114:115], v[104:105], v[104:105]
	v_or_b32_e32 v112, 16, v144
	v_max_f32_e32 v106, 0, v106
	v_ashrrev_i32_e32 v113, 31, v112
	v_max_f32_e32 v108, 0, v108
	v_max_f32_e32 v109, 0, v109
	v_max_f32_e32 v104, 0, v110
	v_max_f32_e32 v105, 0, v111
	v_max_f32_e32 v107, 0, v107
	v_lshlrev_b64 v[112:113], 13, v[112:113]
	v_pk_mul_f32 v[108:109], v[108:109], v[108:109]
	v_pk_mul_f32 v[110:111], v[104:105], v[104:105]
	v_pk_mul_f32 v[116:117], v[106:107], v[106:107]
	v_lshl_add_u64 v[112:113], v[146:147], 0, v[112:113]
	v_cvt_pk_bf16_f32 v104, v108, v109
	v_cvt_pk_bf16_f32 v105, v110, v111
	v_cvt_pk_bf16_f32 v106, v114, v115
	v_cvt_pk_bf16_f32 v107, v116, v117
	v_max_f32_e32 v96, 0, v96
	v_max_f32_e32 v97, 0, v97
	global_store_dwordx4 v[112:113], v[104:107], off nt
	s_nop 1
	v_pk_mul_f32 v[104:105], v[96:97], v[96:97]
	v_max_f32_e32 v98, 0, v98
	v_max_f32_e32 v100, 0, v100
	v_max_f32_e32 v101, 0, v101
	v_max_f32_e32 v96, 0, v102
	v_max_f32_e32 v97, 0, v103
	v_max_f32_e32 v99, 0, v99
	v_pk_mul_f32 v[100:101], v[100:101], v[100:101]
	v_pk_mul_f32 v[102:103], v[96:97], v[96:97]
	v_pk_mul_f32 v[106:107], v[98:99], v[98:99]
	v_cvt_pk_bf16_f32 v96, v100, v101
	v_cvt_pk_bf16_f32 v97, v102, v103
	v_cvt_pk_bf16_f32 v98, v104, v105
	v_cvt_pk_bf16_f32 v99, v106, v107
	v_max_f32_e32 v88, 0, v88
	v_max_f32_e32 v89, 0, v89
	global_store_dwordx4 v[112:113], v[96:99], off offset:256 nt
	s_nop 1
	v_pk_mul_f32 v[98:99], v[88:89], v[88:89]
	v_or_b32_e32 v96, 32, v144
	v_max_f32_e32 v90, 0, v90
	v_ashrrev_i32_e32 v97, 31, v96
	v_max_f32_e32 v92, 0, v92
	v_max_f32_e32 v93, 0, v93
	v_max_f32_e32 v88, 0, v94
	v_max_f32_e32 v89, 0, v95
	v_max_f32_e32 v91, 0, v91
	v_lshlrev_b64 v[96:97], 13, v[96:97]
	v_pk_mul_f32 v[92:93], v[92:93], v[92:93]
	v_pk_mul_f32 v[94:95], v[88:89], v[88:89]
	v_pk_mul_f32 v[100:101], v[90:91], v[90:91]
	v_lshl_add_u64 v[96:97], v[146:147], 0, v[96:97]
	v_cvt_pk_bf16_f32 v88, v92, v93
	v_cvt_pk_bf16_f32 v89, v94, v95
	v_cvt_pk_bf16_f32 v90, v98, v99
	v_cvt_pk_bf16_f32 v91, v100, v101
	v_max_f32_e32 v80, 0, v80
	v_max_f32_e32 v81, 0, v81
	global_store_dwordx4 v[96:97], v[88:91], off nt
	s_nop 1
	v_pk_mul_f32 v[88:89], v[80:81], v[80:81]
	v_max_f32_e32 v82, 0, v82
	v_max_f32_e32 v84, 0, v84
	v_max_f32_e32 v85, 0, v85
	v_max_f32_e32 v80, 0, v86
	v_max_f32_e32 v81, 0, v87
	v_max_f32_e32 v83, 0, v83
	v_pk_mul_f32 v[84:85], v[84:85], v[84:85]
	v_pk_mul_f32 v[86:87], v[80:81], v[80:81]
	v_pk_mul_f32 v[90:91], v[82:83], v[82:83]
	v_cvt_pk_bf16_f32 v80, v84, v85
	v_cvt_pk_bf16_f32 v81, v86, v87
	v_cvt_pk_bf16_f32 v82, v88, v89
	v_cvt_pk_bf16_f32 v83, v90, v91
	v_max_f32_e32 v72, 0, v72
	v_max_f32_e32 v73, 0, v73
	global_store_dwordx4 v[96:97], v[80:83], off offset:256 nt
	s_nop 1
	v_pk_mul_f32 v[82:83], v[72:73], v[72:73]
	v_or_b32_e32 v80, 48, v144
	v_max_f32_e32 v74, 0, v74
	v_ashrrev_i32_e32 v81, 31, v80
	v_max_f32_e32 v76, 0, v76
	v_max_f32_e32 v77, 0, v77
	v_max_f32_e32 v72, 0, v78
	v_max_f32_e32 v73, 0, v79
	v_max_f32_e32 v75, 0, v75
	v_lshlrev_b64 v[80:81], 13, v[80:81]
	v_pk_mul_f32 v[76:77], v[76:77], v[76:77]
	v_pk_mul_f32 v[78:79], v[72:73], v[72:73]
	v_pk_mul_f32 v[84:85], v[74:75], v[74:75]
	v_lshl_add_u64 v[80:81], v[146:147], 0, v[80:81]
	v_cvt_pk_bf16_f32 v72, v76, v77
	v_cvt_pk_bf16_f32 v73, v78, v79
	v_cvt_pk_bf16_f32 v74, v82, v83
	v_cvt_pk_bf16_f32 v75, v84, v85
	v_max_f32_e32 v64, 0, v64
	v_max_f32_e32 v65, 0, v65
	global_store_dwordx4 v[80:81], v[72:75], off nt
	s_nop 1
	v_pk_mul_f32 v[72:73], v[64:65], v[64:65]
	v_max_f32_e32 v66, 0, v66
	v_max_f32_e32 v68, 0, v68
	v_max_f32_e32 v69, 0, v69
	v_max_f32_e32 v64, 0, v70
	v_max_f32_e32 v65, 0, v71
	v_max_f32_e32 v67, 0, v67
	v_pk_mul_f32 v[68:69], v[68:69], v[68:69]
	v_pk_mul_f32 v[70:71], v[64:65], v[64:65]
	v_pk_mul_f32 v[74:75], v[66:67], v[66:67]
	v_cvt_pk_bf16_f32 v64, v68, v69
	v_cvt_pk_bf16_f32 v65, v70, v71
	v_cvt_pk_bf16_f32 v66, v72, v73
	v_cvt_pk_bf16_f32 v67, v74, v75
; __device__ __forceinline__ unsigned cvt_pk_bf16(float lo, float hi) { const f32x2 v = (f32x2){lo, hi}; return __builtin_bit_cast(unsigned, __builtin_convertvector(v, bf16v2)); }
;     __device__ __forceinline__ void operator()(f32x4 (&acc)[2][2][4][2], const Unit& u, int wr, int wc, int fr, int fq, LAS unsigned char* xl, int wid, int lane) const {
;     ...
; #pragma unroll
;         for (int ai = 0; ai < 2; ++ai)
; #pragma unroll
;             for (int m = 0; m < 4; ++m) { bf16_t* rowp = base + (size_t)(row0 + ai * HALF + m * 16) * ldc + col0;
; #pragma unroll
;                 for (int bj = 0; bj < 2; ++bj) { f32x4 v0 = acc[ai][bj][m][0], v1 = acc[ai][bj][m][1];
;                     if (MODE == 2) {
; #pragma unroll
;                         for (int e = 0; e < 4; ++e) { const float a = fmaxf(v0[e], 0.f), b = fmaxf(v1[e], 0.f); v0[e] = a * a; v1[e] = b * b; } }
;                     u32x4 w; w.x = cvt_pk_bf16(v0[0], v0[1]); w.y = cvt_pk_bf16(v0[2], v0[3]); w.z = cvt_pk_bf16(v1[0], v1[1]); w.w = cvt_pk_bf16(v1[2], v1[3]);
;                     *(u32x4*)(rowp + bj * HALF) = w; } }
	v_max_f32_e32 v56, 0, v56
	v_max_f32_e32 v57, 0, v57
	global_store_dwordx4 v[80:81], v[64:67], off offset:256 nt
	s_nop 1
	v_pk_mul_f32 v[66:67], v[56:57], v[56:57]
	v_max_f32_e32 v60, 0, v60
	v_max_f32_e32 v61, 0, v61
	v_max_f32_e32 v58, 0, v58
	v_pk_mul_f32 v[60:61], v[60:61], v[60:61]
	v_max_f32_e32 v56, 0, v62
	v_max_f32_e32 v57, 0, v63
	v_max_f32_e32 v59, 0, v59
	s_mov_b32 s13, 0x100000
	v_pk_mul_f32 v[62:63], v[56:57], v[56:57]
	v_pk_mul_f32 v[68:69], v[58:59], v[58:59]
	v_cvt_pk_bf16_f32 v56, v60, v61
	v_add_co_u32_e32 v60, vcc, s13, v138
	v_cvt_pk_bf16_f32 v57, v62, v63
	v_cvt_pk_bf16_f32 v58, v66, v67
	v_cvt_pk_bf16_f32 v59, v68, v69
	v_addc_co_u32_e32 v61, vcc, 0, v139, vcc
	v_max_f32_e32 v48, 0, v48
	v_max_f32_e32 v49, 0, v49
	global_store_dwordx4 v[60:61], v[56:59], off nt
	s_nop 1
	v_pk_mul_f32 v[56:57], v[48:49], v[48:49]
	v_max_f32_e32 v50, 0, v50
	v_max_f32_e32 v52, 0, v52
	v_max_f32_e32 v53, 0, v53
	v_max_f32_e32 v48, 0, v54
	v_max_f32_e32 v49, 0, v55
	v_max_f32_e32 v51, 0, v51
	s_mov_b64 s[22:23], 0x100000
	v_pk_mul_f32 v[52:53], v[52:53], v[52:53]
	v_pk_mul_f32 v[54:55], v[48:49], v[48:49]
	v_pk_mul_f32 v[58:59], v[50:51], v[50:51]
	v_lshl_add_u64 v[64:65], v[138:139], 0, s[22:23]
	v_cvt_pk_bf16_f32 v48, v52, v53
	v_cvt_pk_bf16_f32 v49, v54, v55
	v_cvt_pk_bf16_f32 v50, v56, v57
	v_cvt_pk_bf16_f32 v51, v58, v59
	v_max_f32_e32 v40, 0, v40
	v_max_f32_e32 v41, 0, v41
	global_store_dwordx4 v[64:65], v[48:51], off offset:256 nt
	s_nop 1
	v_pk_mul_f32 v[50:51], v[40:41], v[40:41]
	v_max_f32_e32 v44, 0, v44
	v_max_f32_e32 v45, 0, v45
	v_max_f32_e32 v42, 0, v42
	v_pk_mul_f32 v[44:45], v[44:45], v[44:45]
	v_max_f32_e32 v40, 0, v46
	v_max_f32_e32 v41, 0, v47
	v_max_f32_e32 v43, 0, v43
	s_mov_b32 s13, 0x120000
	v_pk_mul_f32 v[46:47], v[40:41], v[40:41]
	v_pk_mul_f32 v[52:53], v[42:43], v[42:43]
	v_cvt_pk_bf16_f32 v40, v44, v45
	v_add_co_u32_e32 v44, vcc, s13, v138
	v_cvt_pk_bf16_f32 v41, v46, v47
	v_cvt_pk_bf16_f32 v42, v50, v51
	v_cvt_pk_bf16_f32 v43, v52, v53
	v_addc_co_u32_e32 v45, vcc, 0, v139, vcc
	v_max_f32_e32 v32, 0, v32
	v_max_f32_e32 v33, 0, v33
	global_store_dwordx4 v[44:45], v[40:43], off nt
	s_nop 1
	v_pk_mul_f32 v[40:41], v[32:33], v[32:33]
	v_max_f32_e32 v34, 0, v34
	v_max_f32_e32 v36, 0, v36
	v_max_f32_e32 v37, 0, v37
	v_max_f32_e32 v32, 0, v38
	v_max_f32_e32 v33, 0, v39
	v_max_f32_e32 v35, 0, v35
	s_mov_b64 s[22:23], 0x120000
	v_pk_mul_f32 v[36:37], v[36:37], v[36:37]
	v_pk_mul_f32 v[38:39], v[32:33], v[32:33]
	v_pk_mul_f32 v[42:43], v[34:35], v[34:35]
	v_lshl_add_u64 v[48:49], v[138:139], 0, s[22:23]
	v_cvt_pk_bf16_f32 v32, v36, v37
	v_cvt_pk_bf16_f32 v33, v38, v39
	v_cvt_pk_bf16_f32 v34, v40, v41
	v_cvt_pk_bf16_f32 v35, v42, v43
	v_max_f32_e32 v24, 0, v24
	v_max_f32_e32 v25, 0, v25
	global_store_dwordx4 v[48:49], v[32:35], off offset:256 nt
	s_nop 1
	v_pk_mul_f32 v[34:35], v[24:25], v[24:25]
	v_max_f32_e32 v28, 0, v28
	v_max_f32_e32 v29, 0, v29
	v_max_f32_e32 v26, 0, v26
	v_pk_mul_f32 v[28:29], v[28:29], v[28:29]
	v_max_f32_e32 v24, 0, v30
	v_max_f32_e32 v25, 0, v31
	v_max_f32_e32 v27, 0, v27
	s_mov_b32 s13, 0x140000
	v_pk_mul_f32 v[30:31], v[24:25], v[24:25]
	v_pk_mul_f32 v[36:37], v[26:27], v[26:27]
	v_cvt_pk_bf16_f32 v24, v28, v29
	v_add_co_u32_e32 v28, vcc, s13, v138
	v_cvt_pk_bf16_f32 v25, v30, v31
	v_cvt_pk_bf16_f32 v26, v34, v35
	v_cvt_pk_bf16_f32 v27, v36, v37
	v_addc_co_u32_e32 v29, vcc, 0, v139, vcc
	v_max_f32_e32 v16, 0, v16
	v_max_f32_e32 v17, 0, v17
	global_store_dwordx4 v[28:29], v[24:27], off nt
	s_nop 1
	v_pk_mul_f32 v[24:25], v[16:17], v[16:17]
	v_max_f32_e32 v18, 0, v18
	v_max_f32_e32 v20, 0, v20
	v_max_f32_e32 v21, 0, v21
	v_max_f32_e32 v16, 0, v22
	v_max_f32_e32 v17, 0, v23
	v_max_f32_e32 v19, 0, v19
	s_mov_b64 s[22:23], 0x140000
	v_pk_mul_f32 v[20:21], v[20:21], v[20:21]
	v_pk_mul_f32 v[22:23], v[16:17], v[16:17]
	v_pk_mul_f32 v[26:27], v[18:19], v[18:19]
	v_lshl_add_u64 v[32:33], v[138:139], 0, s[22:23]
	v_cvt_pk_bf16_f32 v16, v20, v21
	v_cvt_pk_bf16_f32 v17, v22, v23
	v_cvt_pk_bf16_f32 v18, v24, v25
	v_cvt_pk_bf16_f32 v19, v26, v27
	v_max_f32_e32 v8, 0, v8
	v_max_f32_e32 v9, 0, v9
	global_store_dwordx4 v[32:33], v[16:19], off offset:256 nt
	s_nop 1
	v_pk_mul_f32 v[18:19], v[8:9], v[8:9]
	v_max_f32_e32 v12, 0, v12
	v_max_f32_e32 v13, 0, v13
	v_max_f32_e32 v10, 0, v10
	v_pk_mul_f32 v[12:13], v[12:13], v[12:13]
	v_max_f32_e32 v8, 0, v14
	v_max_f32_e32 v9, 0, v15
	v_max_f32_e32 v11, 0, v11
	s_mov_b32 s13, 0x160000
	v_pk_mul_f32 v[14:15], v[8:9], v[8:9]
	v_pk_mul_f32 v[20:21], v[10:11], v[10:11]
	v_cvt_pk_bf16_f32 v8, v12, v13
	v_add_co_u32_e32 v12, vcc, s13, v138
	v_cvt_pk_bf16_f32 v9, v14, v15
	v_cvt_pk_bf16_f32 v10, v18, v19
	v_cvt_pk_bf16_f32 v11, v20, v21
	v_addc_co_u32_e32 v13, vcc, 0, v139, vcc
	v_max_f32_e32 v0, 0, v0
	v_max_f32_e32 v1, 0, v1
	global_store_dwordx4 v[12:13], v[8:11], off nt
	s_nop 1
	v_pk_mul_f32 v[8:9], v[0:1], v[0:1]
	v_max_f32_e32 v2, 0, v2
	v_max_f32_e32 v4, 0, v4
	v_max_f32_e32 v5, 0, v5
	v_max_f32_e32 v0, 0, v6
	v_max_f32_e32 v1, 0, v7
	v_max_f32_e32 v3, 0, v3
	s_mov_b64 s[22:23], 0x160000
	v_pk_mul_f32 v[4:5], v[4:5], v[4:5]
	v_pk_mul_f32 v[6:7], v[0:1], v[0:1]
	v_pk_mul_f32 v[10:11], v[2:3], v[2:3]
	v_lshl_add_u64 v[16:17], v[138:139], 0, s[22:23]
	v_cvt_pk_bf16_f32 v0, v4, v5
	v_cvt_pk_bf16_f32 v1, v6, v7
	v_cvt_pk_bf16_f32 v2, v8, v9
	v_cvt_pk_bf16_f32 v3, v10, v11
	s_and_b64 vcc, exec, s[4:5]
	s_mov_b64 s[4:5], -1
	global_store_dwordx4 v[16:17], v[0:3], off offset:256 nt
	s_cbranch_vccnz .LBB0_177
	s_andn2_b64 vcc, exec, s[6:7]
	s_cbranch_vccnz .LBB0_176
	s_barrier
	s_branch .LBB0_176

; __device__ __forceinline__ unsigned cvt_pk_bf16(float lo, float hi) { const f32x2 v = (f32x2){lo, hi}; return __builtin_bit_cast(unsigned, __builtin_convertvector(v, bf16v2)); }
;     __device__ __forceinline__ void operator()(f32x4 (&acc)[2][2][4][2], const Unit& u, int wr, int wc, int fr, int fq, LAS unsigned char* xl, int wid, int lane) const {
;         int prow = u.pm, pcol = u.pn; bf16_t* base = O; size_t ldc = (MODE == 0) ? PBW : (MODE == 1 ? DM : FF);
;         if (MODE == 0 && u.pn >= 6) { prow = u.pn - 6; pcol = u.pm; base = O2; ldc = VTP; }
;         const int row0 = prow * BM + wr * 64 + fr, col0 = pcol * BM + wc * 32 + 8 * fq;
;         if (MODE == 1 && u.ks >= 0) {
;             float* pb = part + ((size_t)u.ks * MC + (size_t)(row0 - ML)) * DM + col0;
; #pragma unroll
;             for (int ai = 0; ai < 2; ++ai)
; #pragma unroll
;                 for (int m = 0; m < 4; ++m) { float* rowp = pb + (size_t)(ai * HALF + m * 16) * DM;
; #pragma unroll
;                     for (int bj = 0; bj < 2; ++bj) { *(f32x4*)(rowp + bj * HALF) = acc[ai][bj][m][0]; *(f32x4*)(rowp + bj * HALF + 4) = acc[ai][bj][m][1]; } }
;             return;
;         }
;         if (MODE == 1) { fused_epi(acc, u, wr, wc, fr, fq, xl, wid, lane, f); return; }
; #pragma unroll
;         for (int ai = 0; ai < 2; ++ai)
; #pragma unroll
;             for (int m = 0; m < 4; ++m) { bf16_t* rowp = base + (size_t)(row0 + ai * HALF + m * 16) * ldc + col0;
; #pragma unroll
;                 for (int bj = 0; bj < 2; ++bj) { f32x4 v0 = acc[ai][bj][m][0], v1 = acc[ai][bj][m][1];
;                     if (MODE == 2) {
; #pragma unroll
;                         for (int e = 0; e < 4; ++e) { const float a = fmaxf(v0[e], 0.f), b = fmaxf(v1[e], 0.f); v0[e] = a * a; v1[e] = b * b; } }
;                     u32x4 w; w.x = cvt_pk_bf16(v0[0], v0[1]); w.y = cvt_pk_bf16(v0[2], v0[3]); w.z = cvt_pk_bf16(v1[0], v1[1]); w.w = cvt_pk_bf16(v1[2], v1[3]);
;                     *(u32x4*)(rowp + bj * HALF) = w; } }
.LBB0_358:
	s_add_u32 s18, s73, s18
	v_lshl_or_b32 v142, s35, 8, v140
	s_addc_u32 s19, s57, s19
	v_lshl_add_u32 v146, s34, 8, v138
	v_ashrrev_i32_e32 v143, 31, v142
	v_lshl_add_u64 v[142:143], v[142:143], 1, s[18:19]
	v_mad_i64_i32 v[144:145], s[18:19], s16, v146, 0
	v_cvt_pk_bf16_f32 v108, v108, v109
	v_cvt_pk_bf16_f32 v109, v110, v111
	v_cvt_pk_bf16_f32 v110, v104, v105
	v_or_b32_e32 v104, 16, v146
	v_lshl_add_u64 v[144:145], v[144:145], 1, v[142:143]
	v_cvt_pk_bf16_f32 v111, v106, v107
	v_mad_i64_i32 v[104:105], s[18:19], s16, v104, 0
	v_cvt_pk_bf16_f32 v92, v92, v93
	v_cvt_pk_bf16_f32 v93, v94, v95
	v_cvt_pk_bf16_f32 v94, v88, v89
	v_or_b32_e32 v88, 32, v146
	v_cvt_pk_bf16_f32 v124, v124, v125
	v_cvt_pk_bf16_f32 v125, v126, v127
	v_cvt_pk_bf16_f32 v126, v120, v121
	v_cvt_pk_bf16_f32 v127, v122, v123
	global_store_dwordx4 v[144:145], v[108:111], off offset:256 nt
	v_cvt_pk_bf16_f32 v95, v90, v91
	v_mad_i64_i32 v[88:89], s[18:19], s16, v88, 0
	v_lshl_add_u64 v[108:109], v[104:105], 1, v[142:143]
	v_cvt_pk_bf16_f32 v76, v76, v77
	v_cvt_pk_bf16_f32 v77, v78, v79
	v_cvt_pk_bf16_f32 v78, v72, v73
	v_or_b32_e32 v72, 48, v146
	v_cvt_pk_bf16_f32 v68, v68, v69
	v_cvt_pk_bf16_f32 v69, v70, v71
	v_cvt_pk_bf16_f32 v70, v64, v65
	v_add_u32_e32 v64, 0x80, v146
	global_store_dwordx4 v[144:145], v[124:127], off nt
	v_cvt_pk_bf16_f32 v104, v116, v117
	v_cvt_pk_bf16_f32 v105, v118, v119
	v_cvt_pk_bf16_f32 v106, v112, v113
	v_cvt_pk_bf16_f32 v107, v114, v115
	global_store_dwordx4 v[108:109], v[92:95], off offset:256 nt
	v_cvt_pk_bf16_f32 v79, v74, v75
	v_mad_i64_i32 v[72:73], s[18:19], s16, v72, 0
	v_lshl_add_u64 v[92:93], v[88:89], 1, v[142:143]
	v_mad_i64_i32 v[64:65], s[18:19], s16, v64, 0
	v_cvt_pk_bf16_f32 v44, v44, v45
	v_cvt_pk_bf16_f32 v45, v46, v47
	v_cvt_pk_bf16_f32 v46, v40, v41
	v_add_u32_e32 v40, 0x90, v146
	global_store_dwordx4 v[108:109], v[104:107], off nt
	v_cvt_pk_bf16_f32 v88, v100, v101
	v_cvt_pk_bf16_f32 v89, v102, v103
	v_cvt_pk_bf16_f32 v90, v96, v97
	v_cvt_pk_bf16_f32 v91, v98, v99
	global_store_dwordx4 v[92:93], v[76:79], off offset:256 nt
	v_cvt_pk_bf16_f32 v74, v80, v81
	v_cvt_pk_bf16_f32 v75, v82, v83
	v_lshl_add_u64 v[76:77], v[72:73], 1, v[142:143]
	v_cvt_pk_bf16_f32 v72, v84, v85
	v_cvt_pk_bf16_f32 v73, v86, v87
	v_cvt_pk_bf16_f32 v71, v66, v67
	v_lshl_add_u64 v[64:65], v[64:65], 1, v[142:143]
	v_cvt_pk_bf16_f32 v47, v42, v43
	v_mad_i64_i32 v[40:41], s[18:19], s16, v40, 0
	v_cvt_pk_bf16_f32 v28, v28, v29
	v_cvt_pk_bf16_f32 v29, v30, v31
	v_cvt_pk_bf16_f32 v30, v24, v25
	v_add_u32_e32 v24, 0xa0, v146
	global_store_dwordx4 v[92:93], v[88:91], off nt
	global_store_dwordx4 v[76:77], v[72:75], off nt
	global_store_dwordx4 v[76:77], v[68:71], off offset:256 nt
	v_cvt_pk_bf16_f32 v60, v60, v61
	v_cvt_pk_bf16_f32 v61, v62, v63
	v_cvt_pk_bf16_f32 v62, v56, v57
	v_cvt_pk_bf16_f32 v63, v58, v59
	global_store_dwordx4 v[64:65], v[44:47], off offset:256 nt
	v_cvt_pk_bf16_f32 v31, v26, v27
	v_mad_i64_i32 v[24:25], s[18:19], s16, v24, 0
	v_lshl_add_u64 v[44:45], v[40:41], 1, v[142:143]
	v_cvt_pk_bf16_f32 v12, v12, v13
	v_cvt_pk_bf16_f32 v13, v14, v15
	v_cvt_pk_bf16_f32 v14, v8, v9
	v_add_u32_e32 v8, 0xb0, v146
	global_store_dwordx4 v[64:65], v[60:63], off nt
	v_cvt_pk_bf16_f32 v40, v52, v53
	v_cvt_pk_bf16_f32 v41, v54, v55
	v_cvt_pk_bf16_f32 v42, v48, v49
	v_cvt_pk_bf16_f32 v43, v50, v51
	global_store_dwordx4 v[44:45], v[28:31], off offset:256 nt
	v_cvt_pk_bf16_f32 v15, v10, v11
	v_mad_i64_i32 v[8:9], s[16:17], s16, v8, 0
	v_lshl_add_u64 v[28:29], v[24:25], 1, v[142:143]
	global_store_dwordx4 v[44:45], v[40:43], off nt
	v_cvt_pk_bf16_f32 v24, v36, v37
	v_cvt_pk_bf16_f32 v25, v38, v39
	v_cvt_pk_bf16_f32 v26, v32, v33
	v_cvt_pk_bf16_f32 v27, v34, v35
	global_store_dwordx4 v[28:29], v[12:15], off offset:256 nt
	v_cvt_pk_bf16_f32 v10, v16, v17
	v_cvt_pk_bf16_f32 v11, v18, v19
	v_lshl_add_u64 v[12:13], v[8:9], 1, v[142:143]
	v_cvt_pk_bf16_f32 v8, v20, v21
	v_cvt_pk_bf16_f32 v9, v22, v23
	v_cvt_pk_bf16_f32 v4, v4, v5
	v_cvt_pk_bf16_f32 v5, v6, v7
	v_cvt_pk_bf16_f32 v6, v0, v1
	v_cvt_pk_bf16_f32 v7, v2, v3
	s_and_b64 vcc, exec, s[4:5]
	s_mov_b64 s[4:5], -1
	global_store_dwordx4 v[28:29], v[24:27], off nt
	global_store_dwordx4 v[12:13], v[8:11], off nt
	global_store_dwordx4 v[12:13], v[4:7], off offset:256 nt
	s_cbranch_vccnz .LBB0_346
	s_andn2_b64 vcc, exec, s[6:7]
	s_cbranch_vccnz .LBB0_345
	s_barrier
	s_branch .LBB0_345
